# att_tail_batch: attention unit tail P.V block issues its 16 V-fragment LDS reads up front into dead registers with counted waits
# baseline (speedup 1.0000x reference)
; #define ATT_BAR() do { if (ABL & 16) asm volatile("s_waitcnt lgkmcnt(0)" ::: "memory"); else asm volatile("s_waitcnt lgkmcnt(0)\n\ts_barrier" ::: "memory"); } while (0)
; #define ATT_VFR(n, ks) const s16x4 l0##n = vtr(vp + (ks) * 1024), h0##n = vtr(vp + (ks) * 1024 + 512), l1##n = vtr(vp + 4096 + (ks) * 1024), h1##n = vtr(vp + 4096 + (ks) * 1024 + 512)
;     ...
;     { const lds_cptr vp = vp0 + ((NTe - 1) & 3) * SLOTB;
;       ATT_VFR(a, 0); ATT_VFR(b, 1); ATT_VFR(c, 2); ATT_VFR(d, 3);
;       ATT_PVK(a, pa0, pb0); ATT_PVK(b, pa1, pb1); ATT_PVK(c, pa2, pb2); ATT_PVK(d, pa3, pb3); }
;     ATT_BAR();
.LBB0_368:
	s_not_b32 s14, s14
	s_lshl_b32 s14, s14, 13
	s_and_b32 s14, s14, 0x6000
	v_add_u32_e32 v104, s14, v191
	ds_read_b64_tr_b16 v[92:93], v104 offset:32768
	ds_read_b64_tr_b16 v[94:95], v104 offset:33280
	ds_read_b64_tr_b16 v[96:97], v104 offset:36864
	ds_read_b64_tr_b16 v[98:99], v104 offset:37376
	ds_read_b64_tr_b16 v[112:113], v104 offset:33792
	ds_read_b64_tr_b16 v[114:115], v104 offset:34304
	ds_read_b64_tr_b16 v[116:117], v104 offset:37888
	ds_read_b64_tr_b16 v[118:119], v104 offset:38400
	ds_read_b64_tr_b16 v[120:121], v104 offset:34816
	ds_read_b64_tr_b16 v[122:123], v104 offset:35328
	ds_read_b64_tr_b16 v[124:125], v104 offset:38912
	ds_read_b64_tr_b16 v[126:127], v104 offset:39424
	ds_read_b64_tr_b16 v[108:109], v104 offset:35840
	ds_read_b64_tr_b16 v[110:111], v104 offset:36352
	ds_read_b64_tr_b16 v[106:107], v104 offset:40448
	ds_read_b64_tr_b16 v[104:105], v104 offset:39936
	v_readlane_b32 s22, v255, 11
	s_cmpk_lt_u32 s17, 0x100
	v_readlane_b32 s23, v255, 12
	s_waitcnt lgkmcnt(14)
	v_mfma_f32_32x32x16_bf16 v[48:63], v[88:91], v[92:95], v[48:63]
	v_readlane_b32 s20, v255, 13
	v_readlane_b32 s21, v255, 14
	s_waitcnt lgkmcnt(12)
	v_mfma_f32_32x32x16_bf16 v[32:47], v[88:91], v[96:99], v[32:47]
	v_mfma_f32_32x32x16_bf16 v[16:31], v[100:103], v[92:95], v[16:31]
	v_mfma_f32_32x32x16_bf16 v[0:15], v[100:103], v[96:99], v[0:15]
	s_waitcnt lgkmcnt(10)
	v_mfma_f32_32x32x16_bf16 v[48:63], v[76:79], v[112:115], v[48:63]
	s_waitcnt lgkmcnt(8)
	v_mfma_f32_32x32x16_bf16 v[32:47], v[76:79], v[116:119], v[32:47]
	v_mfma_f32_32x32x16_bf16 v[16:31], v[84:87], v[112:115], v[16:31]
	v_mfma_f32_32x32x16_bf16 v[0:15], v[84:87], v[116:119], v[0:15]
	s_waitcnt lgkmcnt(6)
	v_mfma_f32_32x32x16_bf16 v[48:63], v[72:75], v[120:123], v[48:63]
	s_waitcnt lgkmcnt(4)
	v_mfma_f32_32x32x16_bf16 v[32:47], v[72:75], v[124:127], v[32:47]
	v_mfma_f32_32x32x16_bf16 v[16:31], v[80:83], v[120:123], v[16:31]
	s_waitcnt lgkmcnt(0)
	s_barrier
	v_mfma_f32_32x32x16_bf16 v[0:15], v[80:83], v[124:127], v[0:15]
	v_mfma_f32_32x32x16_bf16 v[48:63], v[68:71], v[108:111], v[48:63]
	v_mfma_f32_32x32x16_bf16 v[32:47], v[68:71], v[104:107], v[32:47]
	v_mfma_f32_32x32x16_bf16 v[16:31], v[64:67], v[108:111], v[16:31]
	v_mfma_f32_32x32x16_bf16 v[0:15], v[64:67], v[104:107], v[0:15]
	s_cbranch_scc0 .LBB0_370
	s_waitcnt lgkmcnt(0)
	s_barrier
